# P5: conv weights (all 16 quads, one per lane) and the tile's ssq rows fetched at the top of each tile into idle registers (before the K-loop); epilogue issues no global loads and does not wait on vmcn
# speedup vs baseline: 1.0208x; 1.0130x over previous
;     __device__ __forceinline__ bool next(int i, Unit& u) const { u.z = 0; return o.tile(i, u); }
;     __device__ __forceinline__ long a_off(const Unit& u) const { return (long)u.pm * tA; }
;     __device__ __forceinline__ long b_off(const Unit& u) const { return (long)u.pn * tB; }
;     __device__ __forceinline__ bool next(int i, Unit& u) const { u.z = i & 1; return o.tile(i >> 1, u); }
;     __device__ __forceinline__ long a_off(const Unit& u) const { return (long)u.pm * 256 * DM * 2 + (long)u.z * 512 * 2; }
;     __device__ __forceinline__ long b_off(const Unit& u) const { return ((long)u.z * 1024 + (long)u.pn * 256) * 512 * 2; }
;     __device__ __forceinline__ bool next(int i, Unit& u) const { u.z = 0; return o.tile(i, u); }
;     __device__ __forceinline__ long a_off(const Unit& u) const { const int ti = u.pm; const int b = ti / 65, i = ti % 65; return ((long)b * SEQ + 254 * i - 2) * DM * 2; }
;     __device__ __forceinline__ long b_off(const Unit& u) const { return (long)u.pn * 256 * DM * 2; }
;     __device__ bool tile(int i, Unit& u) const {
;         const long L = (long)i * G + c; if (L >= nwg) return false;
;         int wgid = (int)L; { const int q = nwg / NXCD, r = nwg % NXCD, xcd = wgid % NXCD, off = wgid / NXCD; wgid = (xcd < r ? xcd * (q + 1) : r * (q + 1) + (xcd - r) * q) + off; }
;         const int nig = WGM * nN, gid = wgid / nig, fm = gid * WGM, gsz = (nM - fm) < WGM ? (nM - fm) : WGM;
;         u.pm = fm + ((wgid % nig) % gsz); u.pn = (wgid % nig) / gsz; return true;
; template <class Epi, class Sched>
; __device__ __forceinline__ void gemm_phase(LAS unsigned char* lds, const Gemm g, const Sched& S, const Epi& E) {
;     ...
;         const bool has_next = S.next(ui + 1, nxt);
;         const char* nA = has_next ? (const char*)g.A + S.a_off(nxt) : cA; const char* nB = has_next ? (const char*)g.Bt + S.b_off(nxt) : cB;
.LBB0_1022:
	v_readlane_b32 s3, v246, 38
	s_lshl_b32 s10, s22, 7
	s_or_b32 s3, s3, s10
	v_lshlrev_b32_e32 v214, 3, v230
	v_add_u32_e32 v214, s3, v214
	v_bfe_u32 v215, v229, 3, 1
	v_lshl_add_u32 v214, v215, 2, v214
	v_bfe_u32 v215, v229, 2, 1
	v_mul_u32_u24_e32 v215, 0x2c00, v215
	v_lshl_add_u32 v220, v214, 2, v215
	v_mov_b32_e32 v221, 0
	v_and_b32_e32 v214, 3, v229
	v_max_u32_e32 v215, 1, v214
	v_add_u32_e32 v215, 0xffffffff, v215
	v_mov_b64_e32 v[218:219], s[40:41]
	s_movk_i32 s3, 0x5800
	v_mad_u64_u32 v[218:219], s[10:11], v215, s3, v[218:219]
	v_mov_b64_e32 v[216:217], s[44:45]
	v_cmp_eq_u32_e64 s[10:11], 0, v214
	s_nop 1
	v_cndmask_b32_e64 v218, v218, v216, s[10:11]
	v_cndmask_b32_e64 v219, v219, v217, s[10:11]
	v_lshl_add_u64 v[218:219], v[218:219], 0, v[220:221]
	global_load_dwordx4 v[250:253], v[218:219], off
	v_readlane_b32 s3, v246, 30
	s_lshl_b32 s10, s16, 8
	s_add_i32 s3, s3, s10
	v_lshl_add_u32 v214, v229, 2, s3
	v_mov_b32_e32 v215, 0
	v_readlane_b32 s10, v246, 20
	v_readlane_b32 s11, v246, 21
	s_nop 1
	v_lshl_add_u64 v[214:215], v[214:215], 2, s[10:11]
	global_load_dwordx4 v[194:197], v[214:215], off
	global_load_dwordx4 v[198:201], v[214:215], off offset:512
	s_add_i32 s31, s31, 1
	v_readlane_b32 s3, v247, 17
	v_readlane_b32 s10, v246, 9
	s_mul_i32 s3, s31, s3
	s_mul_hi_u32 s9, s31, s10
	s_add_i32 s9, s9, s3
	s_mul_i32 s3, s31, s10
	v_readlane_b32 s10, v246, 8
	v_readlane_b32 s11, v246, 10
	s_add_u32 s10, s3, s10
	v_readlane_b32 s3, v247, 16
	s_addc_u32 s11, s9, s3
	v_cmp_gt_i64_e32 vcc, s[10:11], v[204:205]
	v_cmp_lt_i64_e64 s[46:47], s[10:11], v[202:203]
	s_cbranch_vccnz .LBB0_1024
	s_ashr_i32 s2, s10, 31
	s_lshr_b32 s2, s2, 29
	s_add_i32 s2, s10, s2
	s_ashr_i32 s3, s2, 3
	s_and_b32 s2, s2, -8
	s_sub_i32 s2, s10, s2
	s_cmp_lt_i32 s2, 0
	s_movk_i32 s8, 0x161
	s_cselect_b32 s8, s8, 0x160
	s_mul_i32 s2, s2, s8
	s_add_i32 s2, s2, s3
	s_mul_hi_i32 s3, s2, 0x2e8ba2e9
	s_lshr_b32 s8, s3, 31
	s_ashr_i32 s3, s3, 5
	s_add_i32 s3, s3, s8
	s_lshl_b32 s8, s3, 3
	s_sub_i32 s9, 0x80, s8
	s_min_i32 s9, s9, 8
	s_abs_i32 s10, s9
	v_cvt_f32_u32_e32 v0, s10
	s_sub_i32 s12, 0, s10
	s_mulk_i32 s3, 0xb0
	s_sub_i32 s3, s2, s3
	v_rcp_iflag_f32_e32 v0, v0
	s_abs_i32 s2, s3
	s_xor_b32 s11, s3, s9
	s_ashr_i32 s11, s11, 31
	v_mul_f32_e32 v0, 0x4f7ffffe, v0
	v_cvt_u32_f32_e32 v0, v0
	s_nop 0
	v_readfirstlane_b32 s13, v0
	s_mul_i32 s12, s12, s13
	s_mul_hi_u32 s12, s13, s12
	s_add_i32 s13, s13, s12
	s_mul_hi_u32 s12, s2, s13
	s_mul_i32 s13, s12, s10
	s_sub_i32 s2, s2, s13
	s_add_i32 s17, s12, 1
	s_sub_i32 s13, s2, s10
	s_cmp_ge_u32 s2, s10
	s_cselect_b32 s12, s17, s12
	s_cselect_b32 s2, s13, s2
	s_add_i32 s13, s12, 1
	s_cmp_ge_u32 s2, s10
	s_cselect_b32 s2, s13, s12
	s_xor_b32 s2, s2, s11
	s_sub_i32 s2, s2, s11
	s_mul_i32 s9, s2, s9
	s_sub_i32 s3, s3, s9
	s_add_i32 s8, s8, s3

;     __device__ __forceinline__ void operator()(AccT& acc, const Unit& u, int wr, int wc, int fr, int fq) const {
;         const int b = u.pm >> 6, tstart = (u.pm & 63) * 256;
;         const long arow0 = (long)u.pm * 256;
;         const int colg0 = u.pn * 128 + wc * 32 + fq * 8;
;         f32x4 cwg[2][3], cwv[2][3], cbg[2], cbv[2];
; #pragma unroll
;         for (int n = 0; n < 1; ++n) { const int colg = colg0 + n * 4, colv = FF + colg;
; #pragma unroll
;             for (int j = 0; j < 3; ++j) { cwg[n][j] = *(const f32x4*)(cw + j * FF2 + colg); cwv[n][j] = *(const f32x4*)(cw + j * FF2 + colv); }
;             cbg[n] = *(const f32x4*)(cb + colg); cbv[n] = *(const f32x4*)(cb + colv); }
;         float sq[2][4];
; #pragma unroll
;         for (int ai = 0; ai < 2; ++ai)
; #pragma unroll
;             for (int m = 0; m < 4; ++m) { const int rl = ai * 128 + wr * 64 + m * 16 + fr, t = tstart + rl; sq[ai][m] = ssq[arow0 + rl]; }
; #pragma unroll
;         for (int ai = 0; ai < 2; ++ai)
; #pragma unroll
;             for (int m = 0; m < 4; ++m) {
;                 const int rl = ai * 128 + wr * 64 + m * 16 + fr;
;                 const int t = tstart + rl;
;                 const float rs = __builtin_amdgcn_rsqf(sq[ai][m] * (1.0f / 1024.0f) + EPS);
; #pragma unroll
;                 for (int bj = 0; bj < 2; ++bj)
; #pragma unroll
;                     for (int n = 0; n < 2; ++n) acc[ai][bj][m][n] = acc[ai][bj][m][n] * rs;
;             }
.LBB0_1028:
	s_lshl_b32 s3, s22, 7
	v_readlane_b32 s9, v246, 38
	s_ashr_i32 s17, s16, 31
	v_readlane_b32 s18, v246, 20
	v_readlane_b32 s19, v246, 21
	v_readlane_b32 s20, v246, 30
	s_or_b32 s3, s3, s9
	v_lshlrev_b32_e32 v182, 3, v230
	v_mov_b32_e32 v183, 0
	v_mov_b32_e32 v193, 0
	v_add_u32_e32 v182, s3, v182
	s_lshl_b64 s[14:15], s[16:17], 10
	v_lshl_add_u32 v192, v229, 2, s20
	s_add_u32 s14, s18, s14
	s_addc_u32 s15, s19, s15
	v_cmp_eq_u32_e64 s[48:49], 0, v229
	v_cmp_eq_u32_e64 s[50:51], 15, v229
	s_cmp_eq_u32 s20, 0
	s_cselect_b64 s[54:55], -1, 0
	s_cselect_b64 s[72:73], 0, -1
	s_mov_b64 s[52:53], 0x2000
	s_and_b64 s[74:75], s[48:49], s[54:55]
	s_and_b64 s[76:77], s[50:51], s[72:73]
	s_and_b64 s[80:81], s[48:49], s[72:73]
	s_lshl_b64 s[16:17], s[16:17], 8
	v_lshl_add_u64 v[184:185], s[16:17], 0, v[192:193]
	v_mov_b64_e32 v[216:217], s[84:85]
	s_movk_i32 s3, 0x1600
	v_mad_u64_u32 v[216:217], s[22:23], v184, s3, v[216:217]
	v_mad_i32_i24 v217, v185, s3, v217
	v_lshl_add_u64 v[184:185], v[182:183], 1, v[216:217]
	s_mov_b32 s56, 0
	s_mov_b32 s57, 0
	s_mov_b32 s58, 5632
	s_mov_b32 s59, 0
	s_mov_b32 s60, 11264
	s_mov_b32 s61, 0
	s_mov_b32 s62, 16896
	s_mov_b32 s63, 0
	s_mov_b32 s64, 720896
	s_mov_b32 s65, 0
	s_mov_b32 s66, 726528
	s_mov_b32 s67, 0
	s_mov_b32 s68, 732160
	s_mov_b32 s69, 0
	s_mov_b32 s70, 737792
	s_mov_b32 s71, 0
	s_lshl_b32 s3, s20, 5
	s_lshl_b32 s9, s9, 4
	s_add_i32 s3, s3, s9
	s_add_i32 s3, s3, 0x20000
	v_lshl_add_u32 v189, v230, 7, s3
	s_lshl_b32 s9, s9, 1
	s_add_i32 s9, s9, 0x22000
	v_lshl_add_u32 v255, v230, 8, s9
	v_lshl_add_u32 v254, v229, 4, v255
	ds_write_b128 v254, v[250:253]
	s_nop 1
	v_add_u32_e32 v188, 0xfffff800, v189
	v_mov_b32_e32 v186, 0xbf3a00e3
	v_fmamk_f32 v126, v194, 0x3a800000, v223
	v_rsq_f32_e32 v126, v126
	s_nop 0
	v_pk_mul_f32 v[160:161], v[160:161], v[126:127] op_sel_hi:[1,0]
	v_pk_mul_f32 v[162:163], v[162:163], v[126:127] op_sel_hi:[1,0]
	v_pk_mul_f32 v[60:61], v[60:61], v[126:127] op_sel_hi:[1,0]
	v_pk_mul_f32 v[62:63], v[62:63], v[126:127] op_sel_hi:[1,0]
	v_pk_mul_f32 v[156:157], v[156:157], v[126:127] op_sel_hi:[1,0]
	v_pk_mul_f32 v[158:159], v[158:159], v[126:127] op_sel_hi:[1,0]
	v_pk_mul_f32 v[56:57], v[56:57], v[126:127] op_sel_hi:[1,0]
	v_pk_mul_f32 v[58:59], v[58:59], v[126:127] op_sel_hi:[1,0]
	v_fmamk_f32 v126, v195, 0x3a800000, v223
	v_rsq_f32_e32 v126, v126
	s_nop 0
	v_pk_mul_f32 v[144:145], v[144:145], v[126:127] op_sel_hi:[1,0]
	v_pk_mul_f32 v[146:147], v[146:147], v[126:127] op_sel_hi:[1,0]
	v_pk_mul_f32 v[52:53], v[52:53], v[126:127] op_sel_hi:[1,0]
	v_pk_mul_f32 v[54:55], v[54:55], v[126:127] op_sel_hi:[1,0]
	v_pk_mul_f32 v[118:119], v[118:119], v[126:127] op_sel_hi:[1,0]
	v_pk_mul_f32 v[120:121], v[120:121], v[126:127] op_sel_hi:[1,0]
	v_pk_mul_f32 v[40:41], v[40:41], v[126:127] op_sel_hi:[1,0]
	v_pk_mul_f32 v[42:43], v[42:43], v[126:127] op_sel_hi:[1,0]
	v_fmamk_f32 v126, v196, 0x3a800000, v223
	v_rsq_f32_e32 v126, v126
	s_nop 0
	v_pk_mul_f32 v[140:141], v[140:141], v[126:127] op_sel_hi:[1,0]
	v_pk_mul_f32 v[142:143], v[142:143], v[126:127] op_sel_hi:[1,0]
	v_pk_mul_f32 v[36:37], v[36:37], v[126:127] op_sel_hi:[1,0]
	v_pk_mul_f32 v[38:39], v[38:39], v[126:127] op_sel_hi:[1,0]
	v_pk_mul_f32 v[114:115], v[114:115], v[126:127] op_sel_hi:[1,0]
	v_pk_mul_f32 v[116:117], v[116:117], v[126:127] op_sel_hi:[1,0]
	v_pk_mul_f32 v[32:33], v[32:33], v[126:127] op_sel_hi:[1,0]
	v_pk_mul_f32 v[34:35], v[34:35], v[126:127] op_sel_hi:[1,0]
	v_fmamk_f32 v126, v197, 0x3a800000, v223
	v_rsq_f32_e32 v126, v126
	s_nop 0
	v_pk_mul_f32 v[152:153], v[152:153], v[126:127] op_sel_hi:[1,0]
	v_pk_mul_f32 v[154:155], v[154:155], v[126:127] op_sel_hi:[1,0]
	v_pk_mul_f32 v[48:49], v[48:49], v[126:127] op_sel_hi:[1,0]
	v_pk_mul_f32 v[50:51], v[50:51], v[126:127] op_sel_hi:[1,0]
	v_pk_mul_f32 v[148:149], v[148:149], v[126:127] op_sel_hi:[1,0]
	v_pk_mul_f32 v[150:151], v[150:151], v[126:127] op_sel_hi:[1,0]
	v_pk_mul_f32 v[44:45], v[44:45], v[126:127] op_sel_hi:[1,0]
	v_pk_mul_f32 v[46:47], v[46:47], v[126:127] op_sel_hi:[1,0]
	v_fmamk_f32 v126, v198, 0x3a800000, v223
	v_rsq_f32_e32 v126, v126
	s_nop 0
	v_pk_mul_f32 v[136:137], v[136:137], v[126:127] op_sel_hi:[1,0]
	v_pk_mul_f32 v[138:139], v[138:139], v[126:127] op_sel_hi:[1,0]
	v_pk_mul_f32 v[28:29], v[28:29], v[126:127] op_sel_hi:[1,0]
	v_pk_mul_f32 v[30:31], v[30:31], v[126:127] op_sel_hi:[1,0]
	v_pk_mul_f32 v[132:133], v[132:133], v[126:127] op_sel_hi:[1,0]
	v_pk_mul_f32 v[134:135], v[134:135], v[126:127] op_sel_hi:[1,0]
	v_pk_mul_f32 v[24:25], v[24:25], v[126:127] op_sel_hi:[1,0]
	v_pk_mul_f32 v[26:27], v[26:27], v[126:127] op_sel_hi:[1,0]
	v_fmamk_f32 v126, v199, 0x3a800000, v223
	v_rsq_f32_e32 v126, v126
	s_nop 0
	v_pk_mul_f32 v[76:77], v[76:77], v[126:127] op_sel_hi:[1,0]
	v_pk_mul_f32 v[78:79], v[78:79], v[126:127] op_sel_hi:[1,0]
	v_pk_mul_f32 v[12:13], v[12:13], v[126:127] op_sel_hi:[1,0]
	v_pk_mul_f32 v[14:15], v[14:15], v[126:127] op_sel_hi:[1,0]
	v_pk_mul_f32 v[72:73], v[72:73], v[126:127] op_sel_hi:[1,0]
	v_pk_mul_f32 v[74:75], v[74:75], v[126:127] op_sel_hi:[1,0]
	v_pk_mul_f32 v[8:9], v[8:9], v[126:127] op_sel_hi:[1,0]
	v_pk_mul_f32 v[10:11], v[10:11], v[126:127] op_sel_hi:[1,0]
	v_fmamk_f32 v126, v200, 0x3a800000, v223
	v_rsq_f32_e32 v126, v126
	s_nop 0
	v_pk_mul_f32 v[68:69], v[68:69], v[126:127] op_sel_hi:[1,0]
	v_pk_mul_f32 v[70:71], v[70:71], v[126:127] op_sel_hi:[1,0]
	v_pk_mul_f32 v[4:5], v[4:5], v[126:127] op_sel_hi:[1,0]
	v_pk_mul_f32 v[6:7], v[6:7], v[126:127] op_sel_hi:[1,0]
	v_pk_mul_f32 v[64:65], v[64:65], v[126:127] op_sel_hi:[1,0]
	v_pk_mul_f32 v[66:67], v[66:67], v[126:127] op_sel_hi:[1,0]
	v_pk_mul_f32 v[0:1], v[0:1], v[126:127] op_sel_hi:[1,0]
	v_pk_mul_f32 v[2:3], v[2:3], v[126:127] op_sel_hi:[1,0]
	v_fmamk_f32 v126, v201, 0x3a800000, v223
	v_rsq_f32_e32 v126, v126
	s_nop 0
	v_pk_mul_f32 v[122:123], v[122:123], v[126:127] op_sel_hi:[1,0]
	v_pk_mul_f32 v[124:125], v[124:125], v[126:127] op_sel_hi:[1,0]
	v_pk_mul_f32 v[16:17], v[16:17], v[126:127] op_sel_hi:[1,0]
	v_pk_mul_f32 v[18:19], v[18:19], v[126:127] op_sel_hi:[1,0]
	v_pk_mul_f32 v[128:129], v[128:129], v[126:127] op_sel_hi:[1,0]
	v_pk_mul_f32 v[130:131], v[130:131], v[126:127] op_sel_hi:[1,0]
	v_pk_mul_f32 v[20:21], v[20:21], v[126:127] op_sel_hi:[1,0]
	v_pk_mul_f32 v[22:23], v[22:23], v[126:127] op_sel_hi:[1,0]
	v_mov_b64_e32 v[194:195], 0x200
	v_mov_b64_e32 v[196:197], 0x680
	v_mov_b64_e32 v[198:199], 0x67f
	v_mov_b64_e32 v[200:201], 0x1ff
	s_and_saveexec_b64 s[20:21], s[50:51]
	s_cbranch_execz .Lmy_p5_xw
; #define LAS __attribute__((address_space(3)))
;     __device__ __forceinline__ void operator()(AccT& acc, const Unit& u, int wr, int wc, int fr, int fq) const {
;     ...
;                         *(LAS f32x4*)(xch + (((ai * 2 + wr) * 2 + (fr - 14)) * 256 + bj * 128 + wc * 32 + fq * 8 + n * 4)) = acc[ai][bj][3][n];
;         }
;         asm volatile("s_waitcnt lgkmcnt(0)" ::: "memory"); __builtin_amdgcn_s_barrier(); asm volatile("" ::: "memory");
;         u32x2 stash[2][4];
; #pragma unroll
;         for (int n = 0; n < 2; ++n) {
;             const int colg = colg0 + n * 4, colv = FF + colg;
;             if (n == 1) {
; #pragma unroll
;                 for (int j = 0; j < 3; ++j) { cwg[1][j] = *(const f32x4*)(cw + j * FF2 + colg); cwv[1][j] = *(const f32x4*)(cw + j * FF2 + colv); }
;                 cbg[1] = *(const f32x4*)(cb + colg); cbv[1] = *(const f32x4*)(cb + colv); }
;             const f32x4 w0g = cwg[n][0], w1g = cwg[n][1], w2g = cwg[n][2], bg = cbg[n];
;             const f32x4 w0v = cwv[n][0], w1v = cwv[n][1], w2v = cwv[n][2], bv = cbv[n];
; #pragma unroll
;             for (int ai = 0; ai < 2; ++ai) {
;                 f32x4 hg = (f32x4){0.f, 0.f, 0.f, 0.f}, hv = hg;
;                 const int s = ai * 2 + wr;
;                 if (s > 0 && fr >= 14) {
;                     hg = *(const LAS f32x4*)(xch + (((s - 1) * 2 + (fr - 14)) * 256 + wc * 32 + fq * 8 + n * 4));
;                     hv = *(const LAS f32x4*)(xch + (((s - 1) * 2 + (fr - 14)) * 256 + 128 + wc * 32 + fq * 8 + n * 4));
;                 }
	ds_write_b128 v189, v[140:143]
	ds_write_b128 v189, v[114:117] offset:16
	ds_write_b128 v189, v[36:39] offset:32
	ds_write_b128 v189, v[32:35] offset:48
	ds_write_b128 v189, v[152:155] offset:64
	ds_write_b128 v189, v[148:151] offset:80
	ds_write_b128 v189, v[48:51] offset:96
	ds_write_b128 v189, v[44:47] offset:112
	ds_write_b128 v189, v[68:71] offset:4096
	ds_write_b128 v189, v[64:67] offset:4112
	ds_write_b128 v189, v[4:7] offset:4128
	ds_write_b128 v189, v[0:3] offset:4144
	ds_write_b128 v189, v[122:125] offset:4160
	ds_write_b128 v189, v[128:131] offset:4176
	ds_write_b128 v189, v[16:19] offset:4192
	ds_write_b128 v189, v[20:23] offset:4208
.Lmy_p5_xw:
	s_or_b64 exec, exec, s[20:21]
	s_waitcnt lgkmcnt(0)
	s_barrier
	ds_read_b128 v[98:101], v255
	ds_read_b128 v[102:105], v255 offset:16
	ds_read_b128 v[106:109], v255 offset:32
	ds_read_b128 v[110:113], v255 offset:48
	ds_read_b128 v[84:87], v255 offset:64
	ds_read_b128 v[92:95], v255 offset:80
	ds_read_b128 v[88:91], v255 offset:96
	ds_read_b128 v[80:83], v255 offset:112
	s_waitcnt lgkmcnt(0)
	v_mov_b64_e32 v[164:165], 0
	v_mov_b64_e32 v[166:167], 0
	v_mov_b64_e32 v[168:169], 0
	v_mov_b64_e32 v[170:171], 0
	v_mov_b64_e32 v[234:235], 0
	v_mov_b64_e32 v[236:237], 0
	v_mov_b64_e32 v[250:251], 0
	v_mov_b64_e32 v[252:253], 0
	s_and_saveexec_b64 s[20:21], s[80:81]
	s_cbranch_execz .Lmy_p5_1
	ds_read_b128 v[234:237], v188 offset:0
	ds_read_b128 v[250:253], v188 offset:16
	ds_read_b128 v[164:167], v188 offset:64
	ds_read_b128 v[168:171], v188 offset:80

; #define LAS __attribute__((address_space(3)))
;     __device__ __forceinline__ void operator()(AccT& acc, const Unit& u, int wr, int wc, int fr, int fq) const {
;     ...
;         for (int n = 0; n < 2; ++n) {
;             const int colg = colg0 + n * 4, colv = FF + colg;
;             if (n == 1) {
; #pragma unroll
;                 for (int j = 0; j < 3; ++j) { cwg[1][j] = *(const f32x4*)(cw + j * FF2 + colg); cwv[1][j] = *(const f32x4*)(cw + j * FF2 + colv); }
;                 cbg[1] = *(const f32x4*)(cb + colg); cbv[1] = *(const f32x4*)(cb + colv); }
;             const f32x4 w0g = cwg[n][0], w1g = cwg[n][1], w2g = cwg[n][2], bg = cbg[n];
;             const f32x4 w0v = cwv[n][0], w1v = cwv[n][1], w2v = cwv[n][2], bv = cbv[n];
; #pragma unroll
;             for (int ai = 0; ai < 2; ++ai) {
;                 f32x4 hg = (f32x4){0.f, 0.f, 0.f, 0.f}, hv = hg;
;                 const int s = ai * 2 + wr;
;                 if (s > 0 && fr >= 14) {
;                     hg = *(const LAS f32x4*)(xch + (((s - 1) * 2 + (fr - 14)) * 256 + wc * 32 + fq * 8 + n * 4));
;                     hv = *(const LAS f32x4*)(xch + (((s - 1) * 2 + (fr - 14)) * 256 + 128 + wc * 32 + fq * 8 + n * 4));
;                 }
.Lmy_p5_6:
	s_or_b64 exec, exec, s[22:23]
	ds_read_b128 v[98:101], v255 offset:128
	ds_read_b128 v[102:105], v255 offset:144
	ds_read_b128 v[106:109], v255 offset:160
	ds_read_b128 v[110:113], v255 offset:176
	ds_read_b128 v[84:87], v255 offset:192
	ds_read_b128 v[92:95], v255 offset:208
	ds_read_b128 v[88:91], v255 offset:224
	ds_read_b128 v[80:83], v255 offset:240
	s_waitcnt lgkmcnt(0)
	v_mov_b64_e32 v[164:165], 0
	v_mov_b64_e32 v[166:167], 0
	v_mov_b64_e32 v[168:169], 0
	v_mov_b64_e32 v[170:171], 0
	v_mov_b64_e32 v[234:235], 0
	v_mov_b64_e32 v[236:237], 0
	v_mov_b64_e32 v[250:251], 0
	v_mov_b64_e32 v[252:253], 0
	s_and_saveexec_b64 s[20:21], s[80:81]
	s_cbranch_execz .Lmy_p5_7
	ds_read_b128 v[234:237], v188 offset:32
	ds_read_b128 v[250:253], v188 offset:48
	ds_read_b128 v[164:167], v188 offset:96
	ds_read_b128 v[168:171], v188 offset:112
